# v7 + out-projection epilogue: second half's 12 loads issued with the first half's (before the write-through stores)
# baseline (speedup 1.0000x reference)
; __device__ __forceinline__ float dot4(f32x4 a) { return (a[0] * a[0] + a[1] * a[1]) + (a[2] * a[2] + a[3] * a[3]); }
; __device__ __forceinline__ void store16_wt(void* p, u32x4 v) { asm volatile("global_store_dwordx4 %0, %1, off sc1\n\ts_nop 1" :: "v"(p), "v"(v) : "memory"); }
; __device__ __forceinline__ u32x4 pack8(f32x4 a, f32x4 b) { u32x4 w; w.x = cvt_pk_bf16(a[0], a[1]); w.y = cvt_pk_bf16(a[2], a[3]); w.z = cvt_pk_bf16(b[0], b[1]); w.w = cvt_pk_bf16(b[2], b[3]); return w; }
;     __device__ __forceinline__ void operator()(const f32x4 (&acc)[2][2][4][2], const Unit& u, int wr, int wc, int fr, int fq) const {
;     ...
;         for (int ai = 0; ai < 2; ++ai) {
;             u32x4 xw[4][2]; float rms[4];
; #pragma unroll
;             for (int m = 0; m < 4; ++m) { const int row = row0 + ai * HALF + m * 16; rms[m] = rms1[row];
; #pragma unroll
;                 for (int bj = 0; bj < 2; ++bj) xw[m][bj] = *(const u32x4*)(XB + (size_t)row * 1024 + col0 + bj * HALF); }
; #pragma unroll
;             for (int m = 0; m < 4; ++m) {
;                 const int row = row0 + ai * HALF + m * 16;
;                 float ss = 0.f; const float r = rms[m];
; #pragma unroll
;                 for (int bj = 0; bj < 2; ++bj) { const int col = col0 + bj * HALF; const u32x4 w = xw[m][bj];
;                     const f32x4 a = (f32x4){__builtin_bit_cast(float, w.x << 16), __builtin_bit_cast(float, w.x & 0xffff0000u), __builtin_bit_cast(float, w.y << 16), __builtin_bit_cast(float, w.y & 0xffff0000u)} * r + acc[ai][bj][m][0],
;                                 b = (f32x4){__builtin_bit_cast(float, w.z << 16), __builtin_bit_cast(float, w.z & 0xffff0000u), __builtin_bit_cast(float, w.w << 16), __builtin_bit_cast(float, w.w & 0xffff0000u)} * r + acc[ai][bj][m][1];
;                     ss += dot4(a) + dot4(b);
;                     store16_wt(X1B + (size_t)row * 1024 + col, pack8(a, b)); }
;                 ss += __shfl_xor(ss, 16); ss += __shfl_xor(ss, 32);
;                 if (fq == 0) __hip_atomic_fetch_add(RSS + row, ss, __ATOMIC_RELAXED, __HIP_MEMORY_SCOPE_AGENT);
.LBB0_724:
	v_mbcnt_lo_u32_b32 v165, -1, 0
	v_mbcnt_hi_u32_b32 v165, -1, v165
	s_lshl_b32 s8, s8, 8
	v_ashrrev_i32_e32 v130, 1, v165
	s_lshl_b32 s9, s22, 8
	s_or_b32 s8, s8, s45
	v_and_b32_e32 v130, -8, v130
	s_add_i32 s9, s9, s44
	v_add_u32_e32 v154, s8, v130
	v_and_or_b32 v158, v165, 15, s9
	v_ashrrev_i32_e32 v155, 31, v154
	v_lshlrev_b64 v[188:189], 1, v[154:155]
	v_ashrrev_i32_e32 v159, 31, v158
	v_lshl_add_u64 v[156:157], s[16:17], 0, v[188:189]
	v_lshlrev_b64 v[190:191], 11, v[158:159]
	v_lshl_add_u64 v[130:131], v[156:157], 0, v[190:191]
	v_lshl_add_u64 v[160:161], v[158:159], 2, s[14:15]
	global_load_dwordx4 v[180:183], v[130:131], off
	global_load_dwordx4 v[184:187], v[130:131], off offset:256
	global_load_dword v192, v[160:161], off
	v_or_b32_e32 v174, 16, v158
	v_or_b32_e32 v168, 32, v158
	v_or_b32_e32 v162, 48, v158
	v_ashrrev_i32_e32 v175, 31, v174
	v_ashrrev_i32_e32 v169, 31, v168
	v_ashrrev_i32_e32 v163, 31, v162
	v_lshlrev_b64 v[178:179], 11, v[174:175]
	v_lshlrev_b64 v[172:173], 11, v[168:169]
	v_lshl_add_u64 v[130:131], v[174:175], 2, s[14:15]
	v_lshl_add_u64 v[132:133], v[168:169], 2, s[14:15]
	v_lshl_add_u64 v[134:135], v[162:163], 2, s[14:15]
	v_lshlrev_b64 v[166:167], 11, v[162:163]
	v_lshl_add_u64 v[136:137], v[156:157], 0, v[178:179]
	v_lshl_add_u64 v[138:139], v[156:157], 0, v[172:173]
	v_lshl_add_u64 v[194:195], v[156:157], 0, v[166:167]
	global_load_dword v176, v[130:131], off
	global_load_dwordx4 v[150:153], v[136:137], off
	global_load_dwordx4 v[146:149], v[136:137], off offset:256
	global_load_dword v170, v[132:133], off
	global_load_dwordx4 v[142:145], v[138:139], off
	s_nop 0
	global_load_dwordx4 v[138:141], v[138:139], off offset:256
	s_nop 0
	global_load_dword v164, v[134:135], off
	s_nop 0
	global_load_dwordx4 v[134:137], v[194:195], off
	global_load_dwordx4 v[130:133], v[194:195], off offset:256
	v_lshl_add_u64 v[190:191], s[12:13], 0, v[190:191]
	v_lshl_add_u64 v[188:189], v[190:191], 0, v[188:189]
	v_cmp_gt_u32_e32 vcc, 16, v165
	s_mov_b64 s[24:25], 0x100
	v_add_u32_e32 v250, 0x80, v158
	v_ashrrev_i32_e32 v251, 31, v250
	v_lshlrev_b64 v[252:253], 11, v[250:251]
	v_lshl_add_u64 v[246:247], v[156:157], 0, v[252:253]
	global_load_dwordx4 v[200:203], v[246:247], off
	global_load_dwordx4 v[204:207], v[246:247], off offset:256
	global_load_dword v236, v[160:161], off offset:512
	v_add_u32_e32 v250, 0x90, v158
	v_ashrrev_i32_e32 v251, 31, v250
	v_lshlrev_b64 v[252:253], 11, v[250:251]
	v_lshl_add_u64 v[246:247], v[156:157], 0, v[252:253]
	global_load_dwordx4 v[208:211], v[246:247], off
	global_load_dwordx4 v[212:215], v[246:247], off offset:256
	global_load_dword v238, v[160:161], off offset:576
	v_add_u32_e32 v250, 0xa0, v158
	v_ashrrev_i32_e32 v251, 31, v250
	v_lshlrev_b64 v[252:253], 11, v[250:251]
	v_lshl_add_u64 v[246:247], v[156:157], 0, v[252:253]
	global_load_dwordx4 v[216:219], v[246:247], off
	global_load_dwordx4 v[220:223], v[246:247], off offset:256
	global_load_dword v240, v[160:161], off offset:640
	v_add_u32_e32 v250, 0xb0, v158
	v_ashrrev_i32_e32 v251, 31, v250
	v_lshlrev_b64 v[252:253], 11, v[250:251]
	v_lshl_add_u64 v[246:247], v[156:157], 0, v[252:253]
	global_load_dwordx4 v[224:227], v[246:247], off
	global_load_dwordx4 v[232:235], v[246:247], off offset:256
	global_load_dword v244, v[160:161], off offset:704
	s_waitcnt vmcnt(0)
	v_lshlrev_b32_e32 v190, 16, v180
	v_and_b32_e32 v191, 0xffff0000, v180
	v_lshlrev_b32_e32 v180, 16, v181
	v_and_b32_e32 v181, 0xffff0000, v181
	v_lshlrev_b32_e32 v194, 16, v182
	v_and_b32_e32 v195, 0xffff0000, v182
	v_lshlrev_b32_e32 v182, 16, v183
	v_and_b32_e32 v183, 0xffff0000, v183
	v_lshlrev_b32_e32 v196, 16, v184
	v_and_b32_e32 v197, 0xffff0000, v184
	v_lshlrev_b32_e32 v184, 16, v185
	v_and_b32_e32 v185, 0xffff0000, v185
	v_lshlrev_b32_e32 v198, 16, v186
	v_and_b32_e32 v199, 0xffff0000, v186
	v_lshlrev_b32_e32 v186, 16, v187
	v_and_b32_e32 v187, 0xffff0000, v187
	v_pk_fma_f32 v[128:129], v[192:193], v[180:181], v[128:129] op_sel_hi:[0,1,1]
	v_pk_fma_f32 v[126:127], v[192:193], v[190:191], v[126:127] op_sel_hi:[0,1,1]
	v_pk_fma_f32 v[124:125], v[192:193], v[182:183], v[124:125] op_sel_hi:[0,1,1]
	v_pk_fma_f32 v[122:123], v[192:193], v[194:195], v[122:123] op_sel_hi:[0,1,1]
	v_pk_fma_f32 v[120:121], v[192:193], v[184:185], v[120:121] op_sel_hi:[0,1,1]
	v_pk_fma_f32 v[118:119], v[192:193], v[196:197], v[118:119] op_sel_hi:[0,1,1]
	v_pk_fma_f32 v[180:181], v[192:193], v[186:187], v[116:117] op_sel_hi:[0,1,1]
	v_pk_fma_f32 v[182:183], v[192:193], v[198:199], v[114:115] op_sel_hi:[0,1,1]
	v_mul_f32_e32 v165, v127, v127
	v_mul_f32_e32 v171, v129, v129
	v_mul_f32_e32 v177, v123, v123
	v_mul_f32_e32 v184, v125, v125
	v_cvt_pk_bf16_f32 v114, v126, v127
	v_cvt_pk_bf16_f32 v115, v128, v129
	v_cvt_pk_bf16_f32 v116, v122, v123
	v_cvt_pk_bf16_f32 v117, v124, v125
	v_mul_f32_e32 v123, v119, v119
	v_mul_f32_e32 v125, v121, v121
	v_mul_f32_e32 v127, v183, v183
	v_mul_f32_e32 v129, v181, v181
	v_fmac_f32_e32 v165, v126, v126
	v_fmac_f32_e32 v171, v128, v128
	v_fmac_f32_e32 v177, v122, v122
	v_fmac_f32_e32 v184, v124, v124
	global_store_dwordx4 v[188:189], v[114:117], off sc1
	s_nop 1
	v_fmac_f32_e32 v123, v118, v118
	v_fmac_f32_e32 v125, v120, v120
	v_fmac_f32_e32 v127, v182, v182
	v_add_f32_e32 v114, v165, v171
	v_add_f32_e32 v115, v177, v184
	v_fmac_f32_e32 v129, v180, v180
	v_add_f32_e32 v116, v123, v125
	v_add_f32_e32 v114, v114, v115
	v_add_f32_e32 v115, v127, v129
	v_add_f32_e32 v115, v116, v115
	v_and_b32_e32 v116, 64, v1
	v_add_f32_e32 v115, v114, v115
	v_xor_b32_e32 v114, 16, v1
	v_add_u32_e32 v117, 64, v116
	v_cmp_lt_i32_e64 s[8:9], v114, v117
	v_lshl_add_u64 v[122:123], v[188:189], 0, s[24:25]
	v_cvt_pk_bf16_f32 v118, v118, v119
	v_cndmask_b32_e64 v114, v1, v114, s[8:9]
	v_lshlrev_b32_e32 v114, 2, v114
	ds_bpermute_b32 v116, v114, v115
	v_cvt_pk_bf16_f32 v119, v120, v121
	v_cvt_pk_bf16_f32 v120, v182, v183
	v_cvt_pk_bf16_f32 v121, v180, v181
	global_store_dwordx4 v[122:123], v[118:121], off sc1
	s_nop 1
	s_waitcnt lgkmcnt(0)
	v_add_f32_e32 v116, v115, v116
	v_xor_b32_e32 v115, 32, v1
	v_cmp_lt_i32_e64 s[8:9], v115, v117
	s_nop 1
	v_cndmask_b32_e64 v115, v1, v115, s[8:9]
	v_lshlrev_b32_e32 v115, 2, v115
	ds_bpermute_b32 v117, v115, v116
	s_and_saveexec_b64 s[8:9], vcc
	v_readlane_b32 s56, v255, 9
	v_readlane_b32 s57, v255, 10
	v_readlane_b32 s58, v255, 8
	s_cbranch_execz .LBB0_726
	v_lshl_add_u64 v[118:119], v[158:159], 2, s[10:11]
	s_waitcnt lgkmcnt(0)
	v_add_f32_e32 v116, v116, v117
	global_atomic_add_f32 v[118:119], v116, off

; __device__ __forceinline__ float dot4(f32x4 a) { return (a[0] * a[0] + a[1] * a[1]) + (a[2] * a[2] + a[3] * a[3]); }
; __device__ __forceinline__ void store16_wt(void* p, u32x4 v) { asm volatile("global_store_dwordx4 %0, %1, off sc1\n\ts_nop 1" :: "v"(p), "v"(v) : "memory"); }
; __device__ __forceinline__ u32x4 pack8(f32x4 a, f32x4 b) { u32x4 w; w.x = cvt_pk_bf16(a[0], a[1]); w.y = cvt_pk_bf16(a[2], a[3]); w.z = cvt_pk_bf16(b[0], b[1]); w.w = cvt_pk_bf16(b[2], b[3]); return w; }
;     __device__ __forceinline__ void operator()(const f32x4 (&acc)[2][2][4][2], const Unit& u, int wr, int wc, int fr, int fq) const {
;     ...
;         for (int ai = 0; ai < 2; ++ai) {
;             u32x4 xw[4][2]; float rms[4];
; #pragma unroll
;             for (int m = 0; m < 4; ++m) { const int row = row0 + ai * HALF + m * 16; rms[m] = rms1[row];
; #pragma unroll
;                 for (int bj = 0; bj < 2; ++bj) xw[m][bj] = *(const u32x4*)(XB + (size_t)row * 1024 + col0 + bj * HALF); }
; #pragma unroll
;             for (int m = 0; m < 4; ++m) {
;                 const int row = row0 + ai * HALF + m * 16;
;                 float ss = 0.f; const float r = rms[m];
; #pragma unroll
;                 for (int bj = 0; bj < 2; ++bj) { const int col = col0 + bj * HALF; const u32x4 w = xw[m][bj];
;                     const f32x4 a = (f32x4){__builtin_bit_cast(float, w.x << 16), __builtin_bit_cast(float, w.x & 0xffff0000u), __builtin_bit_cast(float, w.y << 16), __builtin_bit_cast(float, w.y & 0xffff0000u)} * r + acc[ai][bj][m][0],
;                                 b = (f32x4){__builtin_bit_cast(float, w.z << 16), __builtin_bit_cast(float, w.z & 0xffff0000u), __builtin_bit_cast(float, w.w << 16), __builtin_bit_cast(float, w.w & 0xffff0000u)} * r + acc[ai][bj][m][1];
;                     ss += dot4(a) + dot4(b);
;                     store16_wt(X1B + (size_t)row * 1024 + col, pack8(a, b)); }
;                 ss += __shfl_xor(ss, 16); ss += __shfl_xor(ss, 32);
;                 if (fq == 0) __hip_atomic_fetch_add(RSS + row, ss, __ATOMIC_RELAXED, __HIP_MEMORY_SCOPE_AGENT);
.LBB0_732:
	s_or_b64 exec, exec, s[8:9]
	v_add_u32_e32 v108, 0x80, v158
	v_ashrrev_i32_e32 v109, 31, v108
	v_lshlrev_b64 v[120:121], 11, v[108:109]
	s_waitcnt lgkmcnt(0)
	v_add_u32_e32 v102, 0x90, v158
	v_add_u32_e32 v96, 0xa0, v158
	v_add_u32_e32 v90, 0xb0, v158
	v_ashrrev_i32_e32 v103, 31, v102
	v_ashrrev_i32_e32 v97, 31, v96
	v_ashrrev_i32_e32 v91, 31, v90
	v_lshlrev_b64 v[106:107], 11, v[102:103]
	v_lshlrev_b64 v[100:101], 11, v[96:97]
	v_lshlrev_b64 v[94:95], 11, v[90:91]
	v_lshl_add_u64 v[124:125], v[156:157], 0, v[94:95]
	s_nop 0
	v_lshl_add_u64 v[120:121], s[12:13], 0, v[120:121]
	v_lshl_add_u64 v[120:121], v[154:155], 1, v[120:121]
	s_mov_b64 s[8:9], 0x100
	v_lshlrev_b32_e32 v124, 16, v200
	v_and_b32_e32 v125, 0xffff0000, v200
	v_lshlrev_b32_e32 v200, 16, v201
	v_and_b32_e32 v201, 0xffff0000, v201
	v_lshlrev_b32_e32 v126, 16, v202
	v_and_b32_e32 v127, 0xffff0000, v202
	v_lshlrev_b32_e32 v202, 16, v203
	v_and_b32_e32 v203, 0xffff0000, v203
	v_lshlrev_b32_e32 v128, 16, v204
	v_and_b32_e32 v129, 0xffff0000, v204
	v_lshlrev_b32_e32 v204, 16, v205
	v_and_b32_e32 v205, 0xffff0000, v205
	v_lshlrev_b32_e32 v130, 16, v206
	v_and_b32_e32 v131, 0xffff0000, v206
	v_lshlrev_b32_e32 v206, 16, v207
	v_and_b32_e32 v207, 0xffff0000, v207
	v_pk_fma_f32 v[64:65], v[236:237], v[200:201], v[64:65] op_sel_hi:[0,1,1]
	v_pk_fma_f32 v[62:63], v[236:237], v[124:125], v[62:63] op_sel_hi:[0,1,1]
	v_pk_fma_f32 v[60:61], v[236:237], v[202:203], v[60:61] op_sel_hi:[0,1,1]
	v_pk_fma_f32 v[58:59], v[236:237], v[126:127], v[58:59] op_sel_hi:[0,1,1]
	v_pk_fma_f32 v[56:57], v[236:237], v[204:205], v[56:57] op_sel_hi:[0,1,1]
	v_pk_fma_f32 v[54:55], v[236:237], v[128:129], v[54:55] op_sel_hi:[0,1,1]
	v_pk_fma_f32 v[200:201], v[236:237], v[206:207], v[52:53] op_sel_hi:[0,1,1]
	v_pk_fma_f32 v[202:203], v[236:237], v[130:131], v[50:51] op_sel_hi:[0,1,1]
	v_mul_f32_e32 v245, v63, v63
	v_mul_f32_e32 v241, v65, v65
	v_mul_f32_e32 v239, v59, v59
	v_mul_f32_e32 v204, v61, v61
	v_cvt_pk_bf16_f32 v50, v62, v63
	v_cvt_pk_bf16_f32 v51, v64, v65
	v_cvt_pk_bf16_f32 v52, v58, v59
	v_cvt_pk_bf16_f32 v53, v60, v61
	v_mul_f32_e32 v59, v55, v55
	v_mul_f32_e32 v61, v57, v57
	v_mul_f32_e32 v63, v203, v203
	v_mul_f32_e32 v65, v201, v201
	v_fmac_f32_e32 v245, v62, v62
	v_fmac_f32_e32 v241, v64, v64
	v_fmac_f32_e32 v239, v58, v58
	v_fmac_f32_e32 v204, v60, v60
	v_fmac_f32_e32 v59, v54, v54
	v_fmac_f32_e32 v61, v56, v56
	v_fmac_f32_e32 v63, v202, v202
	v_fmac_f32_e32 v65, v200, v200
	global_store_dwordx4 v[120:121], v[50:53], off sc1
	s_nop 1
	v_add_f32_e32 v50, v245, v241
	v_add_f32_e32 v51, v239, v204
	v_add_f32_e32 v52, v59, v61
	v_add_f32_e32 v53, v63, v65
	v_add_f32_e32 v50, v50, v51
	v_add_f32_e32 v51, v52, v53
	v_add_f32_e32 v50, v50, v51
	ds_bpermute_b32 v51, v114, v50
	v_lshl_add_u64 v[58:59], v[120:121], 0, s[8:9]
	v_cvt_pk_bf16_f32 v52, v54, v55
	v_cvt_pk_bf16_f32 v53, v56, v57
	v_cvt_pk_bf16_f32 v54, v202, v203
	s_waitcnt lgkmcnt(0)
	v_add_f32_e32 v50, v50, v51
	ds_bpermute_b32 v51, v115, v50
	v_cvt_pk_bf16_f32 v55, v200, v201
	global_store_dwordx4 v[58:59], v[52:55], off sc1
	s_nop 1
	s_and_saveexec_b64 s[24:25], vcc
	s_cbranch_execz .LBB0_734
	v_lshl_add_u64 v[52:53], v[108:109], 2, s[10:11]
	s_waitcnt lgkmcnt(0)
	v_add_f32_e32 v50, v50, v51
	global_atomic_add_f32 v[52:53], v50, off
.LBB0_734:
	s_or_b64 exec, exec, s[24:25]
	v_lshlrev_b32_e32 v50, 16, v208
	s_waitcnt lgkmcnt(0)
	v_and_b32_e32 v51, 0xffff0000, v208
	v_lshlrev_b32_e32 v52, 16, v209
	v_and_b32_e32 v53, 0xffff0000, v209
	v_pk_fma_f32 v[48:49], v[238:239], v[52:53], v[48:49] op_sel_hi:[0,1,1]
	v_pk_fma_f32 v[46:47], v[238:239], v[50:51], v[46:47] op_sel_hi:[0,1,1]
	v_lshlrev_b32_e32 v50, 16, v210
	v_and_b32_e32 v51, 0xffff0000, v210
	v_lshlrev_b32_e32 v52, 16, v211
	v_and_b32_e32 v53, 0xffff0000, v211
	v_pk_fma_f32 v[52:53], v[238:239], v[52:53], v[44:45] op_sel_hi:[0,1,1]
	v_pk_fma_f32 v[44:45], v[238:239], v[50:51], v[42:43] op_sel_hi:[0,1,1]
	v_mul_f32_e32 v42, v47, v47
	v_mul_f32_e32 v43, v49, v49
	v_fmac_f32_e32 v42, v46, v46
	v_fmac_f32_e32 v43, v48, v48
	v_add_f32_e32 v42, v42, v43
	v_mul_f32_e32 v43, v45, v45
	v_mul_f32_e32 v50, v53, v53
	v_fmac_f32_e32 v43, v44, v44
	v_fmac_f32_e32 v50, v52, v52
	v_add_f32_e32 v43, v43, v50
	v_add_f32_e32 v54, v42, v43
	v_lshl_add_u64 v[42:43], s[12:13], 0, v[106:107]
	v_lshl_add_u64 v[50:51], v[154:155], 1, v[42:43]
	v_cvt_pk_bf16_f32 v42, v46, v47
	v_cvt_pk_bf16_f32 v43, v48, v49
	v_cvt_pk_bf16_f32 v44, v44, v45
	v_cvt_pk_bf16_f32 v45, v52, v53
	global_store_dwordx4 v[50:51], v[42:45], off sc1
	s_nop 1
	v_lshlrev_b32_e32 v42, 16, v212
	v_and_b32_e32 v43, 0xffff0000, v212
	v_lshlrev_b32_e32 v44, 16, v213
	v_and_b32_e32 v45, 0xffff0000, v213
	v_pk_fma_f32 v[40:41], v[238:239], v[44:45], v[40:41] op_sel_hi:[0,1,1]
	v_pk_fma_f32 v[38:39], v[238:239], v[42:43], v[38:39] op_sel_hi:[0,1,1]
	v_lshlrev_b32_e32 v44, 16, v215
	v_and_b32_e32 v45, 0xffff0000, v215
	v_lshlrev_b32_e32 v42, 16, v214
	v_and_b32_e32 v43, 0xffff0000, v214
	v_pk_fma_f32 v[44:45], v[238:239], v[44:45], v[36:37] op_sel_hi:[0,1,1]
	v_mul_f32_e32 v36, v39, v39
	v_mul_f32_e32 v37, v41, v41
	v_pk_fma_f32 v[34:35], v[238:239], v[42:43], v[34:35] op_sel_hi:[0,1,1]
	v_fmac_f32_e32 v36, v38, v38
	v_fmac_f32_e32 v37, v40, v40
	v_add_f32_e32 v36, v36, v37
	v_mul_f32_e32 v37, v35, v35
	v_mul_f32_e32 v42, v45, v45
	v_fmac_f32_e32 v37, v34, v34
	v_fmac_f32_e32 v42, v44, v44
	v_add_f32_e32 v37, v37, v42
	v_add_f32_e32 v36, v36, v37
	v_add_f32_e32 v46, v54, v36
	ds_bpermute_b32 v47, v114, v46
	v_cvt_pk_bf16_f32 v36, v38, v39
	v_cvt_pk_bf16_f32 v38, v34, v35
	v_lshl_add_u64 v[42:43], v[50:51], 0, s[8:9]
	v_cvt_pk_bf16_f32 v37, v40, v41
	s_waitcnt lgkmcnt(0)
	v_add_f32_e32 v34, v46, v47
	ds_bpermute_b32 v35, v115, v34
	v_cvt_pk_bf16_f32 v39, v44, v45
	global_store_dwordx4 v[42:43], v[36:39], off sc1
	s_nop 1
	s_and_saveexec_b64 s[8:9], vcc
	s_cbranch_execz .LBB0_736
	v_lshl_add_u64 v[36:37], v[102:103], 2, s[10:11]
	s_waitcnt lgkmcnt(0)
	v_add_f32_e32 v34, v34, v35
	global_atomic_add_f32 v[36:37], v34, off
; __device__ __forceinline__ float dot4(f32x4 a) { return (a[0] * a[0] + a[1] * a[1]) + (a[2] * a[2] + a[3] * a[3]); }
; __device__ __forceinline__ void store16_wt(void* p, u32x4 v) { asm volatile("global_store_dwordx4 %0, %1, off sc1\n\ts_nop 1" :: "v"(p), "v"(v) : "memory"); }
; __device__ __forceinline__ u32x4 pack8(f32x4 a, f32x4 b) { u32x4 w; w.x = cvt_pk_bf16(a[0], a[1]); w.y = cvt_pk_bf16(a[2], a[3]); w.z = cvt_pk_bf16(b[0], b[1]); w.w = cvt_pk_bf16(b[2], b[3]); return w; }
;     __device__ __forceinline__ void operator()(const f32x4 (&acc)[2][2][4][2], const Unit& u, int wr, int wc, int fr, int fq) const {
;     ...
;         for (int ai = 0; ai < 2; ++ai) {
;             u32x4 xw[4][2]; float rms[4];
; #pragma unroll
;             for (int m = 0; m < 4; ++m) { const int row = row0 + ai * HALF + m * 16; rms[m] = rms1[row];
; #pragma unroll
;                 for (int bj = 0; bj < 2; ++bj) xw[m][bj] = *(const u32x4*)(XB + (size_t)row * 1024 + col0 + bj * HALF); }
; #pragma unroll
;             for (int m = 0; m < 4; ++m) {
;                 const int row = row0 + ai * HALF + m * 16;
;                 float ss = 0.f; const float r = rms[m];
; #pragma unroll
;                 for (int bj = 0; bj < 2; ++bj) { const int col = col0 + bj * HALF; const u32x4 w = xw[m][bj];
;                     const f32x4 a = (f32x4){__builtin_bit_cast(float, w.x << 16), __builtin_bit_cast(float, w.x & 0xffff0000u), __builtin_bit_cast(float, w.y << 16), __builtin_bit_cast(float, w.y & 0xffff0000u)} * r + acc[ai][bj][m][0],
;                                 b = (f32x4){__builtin_bit_cast(float, w.z << 16), __builtin_bit_cast(float, w.z & 0xffff0000u), __builtin_bit_cast(float, w.w << 16), __builtin_bit_cast(float, w.w & 0xffff0000u)} * r + acc[ai][bj][m][1];
;                     ss += dot4(a) + dot4(b);
;                     store16_wt(X1B + (size_t)row * 1024 + col, pack8(a, b)); }
;                 ss += __shfl_xor(ss, 16); ss += __shfl_xor(ss, 32);
;                 if (fq == 0) __hip_atomic_fetch_add(RSS + row, ss, __ATOMIC_RELAXED, __HIP_MEMORY_SCOPE_AGENT);
.LBB0_736:
	s_or_b64 exec, exec, s[8:9]
	v_lshlrev_b32_e32 v34, 16, v216
	s_waitcnt lgkmcnt(0)
	v_and_b32_e32 v35, 0xffff0000, v216
	v_lshlrev_b32_e32 v36, 16, v217
	v_and_b32_e32 v37, 0xffff0000, v217
	v_pk_fma_f32 v[32:33], v[240:241], v[36:37], v[32:33] op_sel_hi:[0,1,1]
	v_pk_fma_f32 v[30:31], v[240:241], v[34:35], v[30:31] op_sel_hi:[0,1,1]
	v_lshlrev_b32_e32 v34, 16, v218
	v_and_b32_e32 v35, 0xffff0000, v218
	v_lshlrev_b32_e32 v36, 16, v219
	v_and_b32_e32 v37, 0xffff0000, v219
	v_pk_fma_f32 v[36:37], v[240:241], v[36:37], v[28:29] op_sel_hi:[0,1,1]
	v_pk_fma_f32 v[28:29], v[240:241], v[34:35], v[26:27] op_sel_hi:[0,1,1]
	v_mul_f32_e32 v26, v31, v31
	v_mul_f32_e32 v27, v33, v33
	v_fmac_f32_e32 v26, v30, v30
	v_fmac_f32_e32 v27, v32, v32
	v_add_f32_e32 v26, v26, v27
	v_mul_f32_e32 v27, v29, v29
	v_mul_f32_e32 v34, v37, v37
	v_fmac_f32_e32 v27, v28, v28
	v_fmac_f32_e32 v34, v36, v36
	v_add_f32_e32 v27, v27, v34
	v_add_f32_e32 v38, v26, v27
	v_lshl_add_u64 v[26:27], s[12:13], 0, v[100:101]
	v_lshl_add_u64 v[34:35], v[154:155], 1, v[26:27]
	v_cvt_pk_bf16_f32 v26, v30, v31
	v_cvt_pk_bf16_f32 v27, v32, v33
	v_cvt_pk_bf16_f32 v28, v28, v29
	v_cvt_pk_bf16_f32 v29, v36, v37
	global_store_dwordx4 v[34:35], v[26:29], off sc1
	s_nop 1
	v_lshlrev_b32_e32 v26, 16, v220
	v_and_b32_e32 v27, 0xffff0000, v220
	v_lshlrev_b32_e32 v28, 16, v221
	v_and_b32_e32 v29, 0xffff0000, v221
	v_pk_fma_f32 v[24:25], v[240:241], v[28:29], v[24:25] op_sel_hi:[0,1,1]
	v_pk_fma_f32 v[22:23], v[240:241], v[26:27], v[22:23] op_sel_hi:[0,1,1]
	v_lshlrev_b32_e32 v28, 16, v223
	v_and_b32_e32 v29, 0xffff0000, v223
	v_lshlrev_b32_e32 v26, 16, v222
	v_and_b32_e32 v27, 0xffff0000, v222
	v_pk_fma_f32 v[28:29], v[240:241], v[28:29], v[20:21] op_sel_hi:[0,1,1]
	v_mul_f32_e32 v20, v23, v23
	v_mul_f32_e32 v21, v25, v25
	v_pk_fma_f32 v[18:19], v[240:241], v[26:27], v[18:19] op_sel_hi:[0,1,1]
	v_fmac_f32_e32 v20, v22, v22
	v_fmac_f32_e32 v21, v24, v24
	v_add_f32_e32 v20, v20, v21
	v_mul_f32_e32 v21, v19, v19
	v_mul_f32_e32 v26, v29, v29
	v_fmac_f32_e32 v21, v18, v18
	v_fmac_f32_e32 v26, v28, v28
	v_add_f32_e32 v21, v21, v26
	v_add_f32_e32 v20, v20, v21
	v_add_f32_e32 v30, v38, v20
	ds_bpermute_b32 v31, v114, v30
	v_cvt_pk_bf16_f32 v20, v22, v23
	v_cvt_pk_bf16_f32 v22, v18, v19
	s_mov_b64 s[8:9], 0x100
	v_lshl_add_u64 v[26:27], v[34:35], 0, s[8:9]
	s_waitcnt lgkmcnt(0)
	v_add_f32_e32 v18, v30, v31
	ds_bpermute_b32 v19, v115, v18
	v_cvt_pk_bf16_f32 v21, v24, v25
	v_cvt_pk_bf16_f32 v23, v28, v29
	global_store_dwordx4 v[26:27], v[20:23], off sc1
	s_nop 1
	s_and_saveexec_b64 s[24:25], vcc
	s_cbranch_execz .LBB0_738
	v_lshl_add_u64 v[20:21], v[96:97], 2, s[10:11]
	s_waitcnt lgkmcnt(0)
	v_add_f32_e32 v18, v18, v19
	global_atomic_add_f32 v[20:21], v18, off
.LBB0_738:
	s_or_b64 exec, exec, s[24:25]
	v_lshlrev_b32_e32 v18, 16, v224
	s_waitcnt lgkmcnt(0)
	v_and_b32_e32 v19, 0xffff0000, v224
	v_lshlrev_b32_e32 v20, 16, v225
	v_and_b32_e32 v21, 0xffff0000, v225
	v_pk_fma_f32 v[16:17], v[244:245], v[20:21], v[16:17] op_sel_hi:[0,1,1]
	v_pk_fma_f32 v[14:15], v[244:245], v[18:19], v[14:15] op_sel_hi:[0,1,1]
	v_lshlrev_b32_e32 v18, 16, v226
	v_and_b32_e32 v19, 0xffff0000, v226
	v_lshlrev_b32_e32 v20, 16, v227
	v_and_b32_e32 v21, 0xffff0000, v227
	v_pk_fma_f32 v[20:21], v[244:245], v[20:21], v[12:13] op_sel_hi:[0,1,1]
	v_pk_fma_f32 v[12:13], v[244:245], v[18:19], v[10:11] op_sel_hi:[0,1,1]
	v_mul_f32_e32 v10, v15, v15
	v_mul_f32_e32 v11, v17, v17
	v_fmac_f32_e32 v10, v14, v14
	v_fmac_f32_e32 v11, v16, v16
	v_add_f32_e32 v10, v10, v11
	v_mul_f32_e32 v11, v13, v13
	v_mul_f32_e32 v18, v21, v21
	v_fmac_f32_e32 v11, v12, v12
	v_fmac_f32_e32 v18, v20, v20
	v_add_f32_e32 v11, v11, v18
	v_add_f32_e32 v22, v10, v11
	v_lshl_add_u64 v[10:11], s[12:13], 0, v[94:95]
	v_lshl_add_u64 v[18:19], v[154:155], 1, v[10:11]
	v_cvt_pk_bf16_f32 v10, v14, v15
	v_cvt_pk_bf16_f32 v11, v16, v17
	v_cvt_pk_bf16_f32 v12, v12, v13
	v_cvt_pk_bf16_f32 v13, v20, v21
	global_store_dwordx4 v[18:19], v[10:13], off sc1
	s_nop 1
	v_lshlrev_b32_e32 v10, 16, v232
	v_and_b32_e32 v11, 0xffff0000, v232
	v_lshlrev_b32_e32 v12, 16, v233
	v_and_b32_e32 v13, 0xffff0000, v233
	v_pk_fma_f32 v[8:9], v[244:245], v[12:13], v[8:9] op_sel_hi:[0,1,1]
	v_pk_fma_f32 v[6:7], v[244:245], v[10:11], v[6:7] op_sel_hi:[0,1,1]
	v_lshlrev_b32_e32 v12, 16, v235
	v_and_b32_e32 v13, 0xffff0000, v235
	v_lshlrev_b32_e32 v10, 16, v234
	v_and_b32_e32 v11, 0xffff0000, v234
	v_pk_fma_f32 v[12:13], v[244:245], v[12:13], v[4:5] op_sel_hi:[0,1,1]
	v_mul_f32_e32 v4, v7, v7
	v_mul_f32_e32 v5, v9, v9
	v_pk_fma_f32 v[2:3], v[244:245], v[10:11], v[2:3] op_sel_hi:[0,1,1]
	v_fmac_f32_e32 v4, v6, v6
	v_fmac_f32_e32 v5, v8, v8
	v_add_f32_e32 v4, v4, v5
	v_mul_f32_e32 v5, v3, v3
	v_mul_f32_e32 v10, v13, v13
	v_fmac_f32_e32 v5, v2, v2
	v_fmac_f32_e32 v10, v12, v12
	v_add_f32_e32 v5, v5, v10
	v_add_f32_e32 v4, v4, v5
	v_add_f32_e32 v14, v22, v4
	ds_bpermute_b32 v15, v114, v14
	v_cvt_pk_bf16_f32 v4, v6, v7
	v_cvt_pk_bf16_f32 v6, v2, v3
	v_lshl_add_u64 v[10:11], v[18:19], 0, s[8:9]
	v_cvt_pk_bf16_f32 v5, v8, v9
	s_waitcnt lgkmcnt(0)
	v_add_f32_e32 v2, v14, v15
	ds_bpermute_b32 v3, v115, v2
	v_cvt_pk_bf16_f32 v7, v12, v13
	global_store_dwordx4 v[10:11], v[4:7], off sc1
	s_nop 1
	s_and_saveexec_b64 s[8:9], vcc
	s_cbranch_execz .LBB0_740
	v_lshl_add_u64 v[4:5], v[90:91], 2, s[10:11]
	s_waitcnt lgkmcnt(0)
	v_add_f32_e32 v2, v2, v3
	global_atomic_add_f32 v[4:5], v2, off

; __device__ __forceinline__ float dot4(f32x4 a) { return (a[0] * a[0] + a[1] * a[1]) + (a[2] * a[2] + a[3] * a[3]); }
; __device__ __forceinline__ void store16_wt(void* p, u32x4 v) { asm volatile("global_store_dwordx4 %0, %1, off sc1\n\ts_nop 1" :: "v"(p), "v"(v) : "memory"); }
; __device__ __forceinline__ u32x4 pack8(f32x4 a, f32x4 b) { u32x4 w; w.x = cvt_pk_bf16(a[0], a[1]); w.y = cvt_pk_bf16(a[2], a[3]); w.z = cvt_pk_bf16(b[0], b[1]); w.w = cvt_pk_bf16(b[2], b[3]); return w; }
;     __device__ __forceinline__ void operator()(const f32x4 (&acc)[2][2][4][2], const Unit& u, int wr, int wc, int fr, int fq) const {
;     ...
;         for (int ai = 0; ai < 2; ++ai) {
;             u32x4 xw[4][2]; float rms[4];
; #pragma unroll
;             for (int m = 0; m < 4; ++m) { const int row = row0 + ai * HALF + m * 16; rms[m] = rms1[row];
; #pragma unroll
;                 for (int bj = 0; bj < 2; ++bj) xw[m][bj] = *(const u32x4*)(XB + (size_t)row * 1024 + col0 + bj * HALF); }
; #pragma unroll
;             for (int m = 0; m < 4; ++m) {
;                 const int row = row0 + ai * HALF + m * 16;
;                 float ss = 0.f; const float r = rms[m];
; #pragma unroll
;                 for (int bj = 0; bj < 2; ++bj) { const int col = col0 + bj * HALF; const u32x4 w = xw[m][bj];
;                     const f32x4 a = (f32x4){__builtin_bit_cast(float, w.x << 16), __builtin_bit_cast(float, w.x & 0xffff0000u), __builtin_bit_cast(float, w.y << 16), __builtin_bit_cast(float, w.y & 0xffff0000u)} * r + acc[ai][bj][m][0],
;                                 b = (f32x4){__builtin_bit_cast(float, w.z << 16), __builtin_bit_cast(float, w.z & 0xffff0000u), __builtin_bit_cast(float, w.w << 16), __builtin_bit_cast(float, w.w & 0xffff0000u)} * r + acc[ai][bj][m][1];
;                     ss += dot4(a) + dot4(b);
;                     store16_wt(X1B + (size_t)row * 1024 + col, pack8(a, b)); }
;                 ss += __shfl_xor(ss, 16); ss += __shfl_xor(ss, 32);
;                 if (fq == 0) __hip_atomic_fetch_add(RSS + row, ss, __ATOMIC_RELAXED, __HIP_MEMORY_SCOPE_AGENT);
.LBB0_770:
	s_lshl_b32 s2, s20, 8
	s_add_i32 s2, s2, s33
	v_mbcnt_lo_u32_b32 v165, -1, 0
	v_mbcnt_hi_u32_b32 v165, -1, v165
	s_nop 0
	v_and_or_b32 v158, v165, 15, s2
	s_lshl_b32 s2, s8, 8
	v_ashrrev_i32_e32 v130, 1, v165
	s_or_b32 s2, s2, s35
	v_and_b32_e32 v130, -8, v130
	v_add_u32_e32 v154, s2, v130
	v_ashrrev_i32_e32 v155, 31, v154
	v_lshlrev_b64 v[188:189], 1, v[154:155]
	v_ashrrev_i32_e32 v159, 31, v158
	v_lshl_add_u64 v[156:157], s[16:17], 0, v[188:189]
	v_lshlrev_b64 v[190:191], 11, v[158:159]
	v_lshl_add_u64 v[130:131], v[156:157], 0, v[190:191]
	v_lshl_add_u64 v[160:161], v[158:159], 2, s[14:15]
	global_load_dwordx4 v[180:183], v[130:131], off
	global_load_dwordx4 v[184:187], v[130:131], off offset:256
	global_load_dword v192, v[160:161], off
	v_or_b32_e32 v174, 16, v158
	v_or_b32_e32 v168, 32, v158
	v_or_b32_e32 v162, 48, v158
	v_ashrrev_i32_e32 v175, 31, v174
	v_ashrrev_i32_e32 v169, 31, v168
	v_ashrrev_i32_e32 v163, 31, v162
	v_lshlrev_b64 v[178:179], 11, v[174:175]
	v_lshlrev_b64 v[172:173], 11, v[168:169]
	v_lshl_add_u64 v[130:131], v[174:175], 2, s[14:15]
	v_lshl_add_u64 v[132:133], v[168:169], 2, s[14:15]
	v_lshl_add_u64 v[134:135], v[162:163], 2, s[14:15]
	v_lshlrev_b64 v[166:167], 11, v[162:163]
	v_lshl_add_u64 v[136:137], v[156:157], 0, v[178:179]
	v_lshl_add_u64 v[138:139], v[156:157], 0, v[172:173]
	v_lshl_add_u64 v[194:195], v[156:157], 0, v[166:167]
	global_load_dword v176, v[130:131], off
	global_load_dwordx4 v[150:153], v[136:137], off
	global_load_dwordx4 v[146:149], v[136:137], off offset:256
	global_load_dword v170, v[132:133], off
	global_load_dwordx4 v[142:145], v[138:139], off
	s_nop 0
	global_load_dwordx4 v[138:141], v[138:139], off offset:256
	s_nop 0
	global_load_dword v164, v[134:135], off
	s_nop 0
	global_load_dwordx4 v[134:137], v[194:195], off
	global_load_dwordx4 v[130:133], v[194:195], off offset:256
	v_lshl_add_u64 v[190:191], s[12:13], 0, v[190:191]
	v_lshl_add_u64 v[188:189], v[190:191], 0, v[188:189]
	v_cmp_gt_u32_e32 vcc, 16, v165
	s_mov_b64 s[14:15], 0x100
	v_add_u32_e32 v250, 0x80, v158
	v_ashrrev_i32_e32 v251, 31, v250
	v_lshlrev_b64 v[252:253], 11, v[250:251]
	v_lshl_add_u64 v[246:247], v[156:157], 0, v[252:253]
	global_load_dwordx4 v[200:203], v[246:247], off
	global_load_dwordx4 v[204:207], v[246:247], off offset:256
	global_load_dword v236, v[160:161], off offset:512
	v_add_u32_e32 v250, 0x90, v158
	v_ashrrev_i32_e32 v251, 31, v250
	v_lshlrev_b64 v[252:253], 11, v[250:251]
	v_lshl_add_u64 v[246:247], v[156:157], 0, v[252:253]
	global_load_dwordx4 v[208:211], v[246:247], off
	global_load_dwordx4 v[212:215], v[246:247], off offset:256
	global_load_dword v238, v[160:161], off offset:576
	v_add_u32_e32 v250, 0xa0, v158
	v_ashrrev_i32_e32 v251, 31, v250
	v_lshlrev_b64 v[252:253], 11, v[250:251]
	v_lshl_add_u64 v[246:247], v[156:157], 0, v[252:253]
	global_load_dwordx4 v[216:219], v[246:247], off
	global_load_dwordx4 v[220:223], v[246:247], off offset:256
	global_load_dword v240, v[160:161], off offset:640
	v_add_u32_e32 v250, 0xb0, v158
	v_ashrrev_i32_e32 v251, 31, v250
	v_lshlrev_b64 v[252:253], 11, v[250:251]
	v_lshl_add_u64 v[246:247], v[156:157], 0, v[252:253]
	global_load_dwordx4 v[224:227], v[246:247], off
	global_load_dwordx4 v[232:235], v[246:247], off offset:256
	global_load_dword v244, v[160:161], off offset:704
	s_waitcnt vmcnt(0)
	v_lshlrev_b32_e32 v190, 16, v180
	v_and_b32_e32 v191, 0xffff0000, v180
	v_lshlrev_b32_e32 v180, 16, v181
	v_and_b32_e32 v181, 0xffff0000, v181
	v_lshlrev_b32_e32 v194, 16, v182
	v_and_b32_e32 v195, 0xffff0000, v182
	v_lshlrev_b32_e32 v182, 16, v183
	v_and_b32_e32 v183, 0xffff0000, v183
	v_lshlrev_b32_e32 v196, 16, v184
	v_and_b32_e32 v197, 0xffff0000, v184
	v_lshlrev_b32_e32 v184, 16, v185
	v_and_b32_e32 v185, 0xffff0000, v185
	v_lshlrev_b32_e32 v198, 16, v186
	v_and_b32_e32 v199, 0xffff0000, v186
	v_lshlrev_b32_e32 v186, 16, v187
	v_and_b32_e32 v187, 0xffff0000, v187
	v_pk_fma_f32 v[128:129], v[192:193], v[180:181], v[128:129] op_sel_hi:[0,1,1]
	v_pk_fma_f32 v[126:127], v[192:193], v[190:191], v[126:127] op_sel_hi:[0,1,1]
	v_pk_fma_f32 v[124:125], v[192:193], v[182:183], v[124:125] op_sel_hi:[0,1,1]
	v_pk_fma_f32 v[122:123], v[192:193], v[194:195], v[122:123] op_sel_hi:[0,1,1]
	v_pk_fma_f32 v[120:121], v[192:193], v[184:185], v[120:121] op_sel_hi:[0,1,1]
	v_pk_fma_f32 v[118:119], v[192:193], v[196:197], v[118:119] op_sel_hi:[0,1,1]
	v_pk_fma_f32 v[180:181], v[192:193], v[186:187], v[116:117] op_sel_hi:[0,1,1]
	v_pk_fma_f32 v[182:183], v[192:193], v[198:199], v[114:115] op_sel_hi:[0,1,1]
	v_mul_f32_e32 v165, v127, v127
	v_mul_f32_e32 v171, v129, v129
	v_mul_f32_e32 v177, v123, v123
	v_mul_f32_e32 v184, v125, v125
	v_cvt_pk_bf16_f32 v114, v126, v127
	v_cvt_pk_bf16_f32 v115, v128, v129
	v_cvt_pk_bf16_f32 v116, v122, v123
	v_cvt_pk_bf16_f32 v117, v124, v125
	v_mul_f32_e32 v123, v119, v119
	v_mul_f32_e32 v125, v121, v121
	v_mul_f32_e32 v127, v183, v183
	v_mul_f32_e32 v129, v181, v181
	v_fmac_f32_e32 v165, v126, v126
	v_fmac_f32_e32 v171, v128, v128
	v_fmac_f32_e32 v177, v122, v122
	v_fmac_f32_e32 v184, v124, v124
	global_store_dwordx4 v[188:189], v[114:117], off sc1
	s_nop 1
	v_fmac_f32_e32 v123, v118, v118
	v_fmac_f32_e32 v125, v120, v120
	v_fmac_f32_e32 v127, v182, v182
	v_add_f32_e32 v114, v165, v171
	v_add_f32_e32 v115, v177, v184
	v_fmac_f32_e32 v129, v180, v180
	v_add_f32_e32 v116, v123, v125
	v_add_f32_e32 v114, v114, v115
	v_add_f32_e32 v115, v127, v129
	v_add_f32_e32 v115, v116, v115
	v_and_b32_e32 v116, 64, v1
	v_add_f32_e32 v115, v114, v115
	v_xor_b32_e32 v114, 16, v1
	v_add_u32_e32 v117, 64, v116
	v_cmp_lt_i32_e64 s[8:9], v114, v117
	v_lshl_add_u64 v[122:123], v[188:189], 0, s[14:15]
	v_cvt_pk_bf16_f32 v118, v118, v119
	v_cndmask_b32_e64 v114, v1, v114, s[8:9]
	v_lshlrev_b32_e32 v114, 2, v114
	ds_bpermute_b32 v116, v114, v115
	v_cvt_pk_bf16_f32 v119, v120, v121
	v_cvt_pk_bf16_f32 v120, v182, v183
	v_cvt_pk_bf16_f32 v121, v180, v181
	global_store_dwordx4 v[122:123], v[118:121], off sc1
	s_nop 1
	s_waitcnt lgkmcnt(0)
	v_add_f32_e32 v116, v115, v116
	v_xor_b32_e32 v115, 32, v1
	v_cmp_lt_i32_e64 s[8:9], v115, v117
	s_nop 1
	v_cndmask_b32_e64 v115, v1, v115, s[8:9]
	v_lshlrev_b32_e32 v115, 2, v115
	ds_bpermute_b32 v117, v115, v116
	s_and_saveexec_b64 s[8:9], vcc
	s_cbranch_execz .LBB0_772
	v_lshl_add_u64 v[118:119], v[158:159], 2, s[10:11]
	s_waitcnt lgkmcnt(0)
	v_add_f32_e32 v116, v116, v117
	global_atomic_add_f32 v[118:119], v116, off

; __device__ __forceinline__ float dot4(f32x4 a) { return (a[0] * a[0] + a[1] * a[1]) + (a[2] * a[2] + a[3] * a[3]); }
; __device__ __forceinline__ void store16_wt(void* p, u32x4 v) { asm volatile("global_store_dwordx4 %0, %1, off sc1\n\ts_nop 1" :: "v"(p), "v"(v) : "memory"); }
; __device__ __forceinline__ u32x4 pack8(f32x4 a, f32x4 b) { u32x4 w; w.x = cvt_pk_bf16(a[0], a[1]); w.y = cvt_pk_bf16(a[2], a[3]); w.z = cvt_pk_bf16(b[0], b[1]); w.w = cvt_pk_bf16(b[2], b[3]); return w; }
;     __device__ __forceinline__ void operator()(const f32x4 (&acc)[2][2][4][2], const Unit& u, int wr, int wc, int fr, int fq) const {
;     ...
;             for (int m = 0; m < 4; ++m) {
;                 const int row = row0 + ai * HALF + m * 16;
;                 float ss = 0.f; const float r = rms[m];
; #pragma unroll
;                 for (int bj = 0; bj < 2; ++bj) { const int col = col0 + bj * HALF; const u32x4 w = xw[m][bj];
;                     const f32x4 a = (f32x4){__builtin_bit_cast(float, w.x << 16), __builtin_bit_cast(float, w.x & 0xffff0000u), __builtin_bit_cast(float, w.y << 16), __builtin_bit_cast(float, w.y & 0xffff0000u)} * r + acc[ai][bj][m][0],
;                                 b = (f32x4){__builtin_bit_cast(float, w.z << 16), __builtin_bit_cast(float, w.z & 0xffff0000u), __builtin_bit_cast(float, w.w << 16), __builtin_bit_cast(float, w.w & 0xffff0000u)} * r + acc[ai][bj][m][1];
;                     ss += dot4(a) + dot4(b);
;                     store16_wt(X1B + (size_t)row * 1024 + col, pack8(a, b)); }
;                 ss += __shfl_xor(ss, 16); ss += __shfl_xor(ss, 32);
;                 if (fq == 0) __hip_atomic_fetch_add(RSS + row, ss, __ATOMIC_RELAXED, __HIP_MEMORY_SCOPE_AGENT);
.LBB0_778:
	s_or_b64 exec, exec, s[8:9]
	v_add_u32_e32 v108, 0x80, v158
	v_ashrrev_i32_e32 v109, 31, v108
	v_lshlrev_b64 v[120:121], 11, v[108:109]
	s_waitcnt lgkmcnt(0)
	v_add_u32_e32 v102, 0x90, v158
	v_add_u32_e32 v96, 0xa0, v158
	v_add_u32_e32 v90, 0xb0, v158
	v_ashrrev_i32_e32 v103, 31, v102
	v_ashrrev_i32_e32 v97, 31, v96
	v_ashrrev_i32_e32 v91, 31, v90
	v_lshlrev_b64 v[106:107], 11, v[102:103]
	v_lshlrev_b64 v[100:101], 11, v[96:97]
	v_lshlrev_b64 v[94:95], 11, v[90:91]
	v_lshl_add_u64 v[124:125], v[156:157], 0, v[94:95]
	s_nop 0
	v_lshl_add_u64 v[120:121], s[12:13], 0, v[120:121]
	v_lshl_add_u64 v[120:121], v[154:155], 1, v[120:121]
	s_mov_b64 s[8:9], 0x100
	v_lshlrev_b32_e32 v124, 16, v200
	v_and_b32_e32 v125, 0xffff0000, v200
	v_lshlrev_b32_e32 v200, 16, v201
	v_and_b32_e32 v201, 0xffff0000, v201
	v_lshlrev_b32_e32 v126, 16, v202
	v_and_b32_e32 v127, 0xffff0000, v202
	v_lshlrev_b32_e32 v202, 16, v203
	v_and_b32_e32 v203, 0xffff0000, v203
	v_lshlrev_b32_e32 v128, 16, v204
	v_and_b32_e32 v129, 0xffff0000, v204
	v_lshlrev_b32_e32 v204, 16, v205
	v_and_b32_e32 v205, 0xffff0000, v205
	v_lshlrev_b32_e32 v130, 16, v206
	v_and_b32_e32 v131, 0xffff0000, v206
	v_lshlrev_b32_e32 v206, 16, v207
	v_and_b32_e32 v207, 0xffff0000, v207
	v_pk_fma_f32 v[64:65], v[236:237], v[200:201], v[64:65] op_sel_hi:[0,1,1]
	v_pk_fma_f32 v[62:63], v[236:237], v[124:125], v[62:63] op_sel_hi:[0,1,1]
	v_pk_fma_f32 v[60:61], v[236:237], v[202:203], v[60:61] op_sel_hi:[0,1,1]
	v_pk_fma_f32 v[58:59], v[236:237], v[126:127], v[58:59] op_sel_hi:[0,1,1]
	v_pk_fma_f32 v[56:57], v[236:237], v[204:205], v[56:57] op_sel_hi:[0,1,1]
	v_pk_fma_f32 v[54:55], v[236:237], v[128:129], v[54:55] op_sel_hi:[0,1,1]
	v_pk_fma_f32 v[200:201], v[236:237], v[206:207], v[52:53] op_sel_hi:[0,1,1]
	v_pk_fma_f32 v[202:203], v[236:237], v[130:131], v[50:51] op_sel_hi:[0,1,1]
	v_mul_f32_e32 v245, v63, v63
	v_mul_f32_e32 v241, v65, v65
	v_mul_f32_e32 v239, v59, v59
	v_mul_f32_e32 v204, v61, v61
	v_cvt_pk_bf16_f32 v50, v62, v63
	v_cvt_pk_bf16_f32 v51, v64, v65
	v_cvt_pk_bf16_f32 v52, v58, v59
	v_cvt_pk_bf16_f32 v53, v60, v61
	v_mul_f32_e32 v59, v55, v55
	v_mul_f32_e32 v61, v57, v57
	v_mul_f32_e32 v63, v203, v203
	v_mul_f32_e32 v65, v201, v201
	v_fmac_f32_e32 v245, v62, v62
	v_fmac_f32_e32 v241, v64, v64
	v_fmac_f32_e32 v239, v58, v58
	v_fmac_f32_e32 v204, v60, v60
	v_fmac_f32_e32 v59, v54, v54
	v_fmac_f32_e32 v61, v56, v56
	v_fmac_f32_e32 v63, v202, v202
	v_fmac_f32_e32 v65, v200, v200
	global_store_dwordx4 v[120:121], v[50:53], off sc1
	s_nop 1
	v_add_f32_e32 v50, v245, v241
	v_add_f32_e32 v51, v239, v204
	v_add_f32_e32 v52, v59, v61
	v_add_f32_e32 v53, v63, v65
	v_add_f32_e32 v50, v50, v51
	v_add_f32_e32 v51, v52, v53
	v_add_f32_e32 v50, v50, v51
	ds_bpermute_b32 v51, v114, v50
	v_lshl_add_u64 v[58:59], v[120:121], 0, s[8:9]
	v_cvt_pk_bf16_f32 v52, v54, v55
	v_cvt_pk_bf16_f32 v53, v56, v57
	v_cvt_pk_bf16_f32 v54, v202, v203
	s_waitcnt lgkmcnt(0)
	v_add_f32_e32 v50, v50, v51
	ds_bpermute_b32 v51, v115, v50
	v_cvt_pk_bf16_f32 v55, v200, v201
	global_store_dwordx4 v[58:59], v[52:55], off sc1
	s_nop 1
	s_and_saveexec_b64 s[14:15], vcc
	s_cbranch_execz .LBB0_780
	v_lshl_add_u64 v[52:53], v[108:109], 2, s[10:11]
	s_waitcnt lgkmcnt(0)
	v_add_f32_e32 v50, v50, v51
	global_atomic_add_f32 v[52:53], v50, off
.LBB0_780:
	s_or_b64 exec, exec, s[14:15]
	v_lshlrev_b32_e32 v50, 16, v208
	s_waitcnt lgkmcnt(0)
	v_and_b32_e32 v51, 0xffff0000, v208
	v_lshlrev_b32_e32 v52, 16, v209
	v_and_b32_e32 v53, 0xffff0000, v209
	v_pk_fma_f32 v[48:49], v[238:239], v[52:53], v[48:49] op_sel_hi:[0,1,1]
	v_pk_fma_f32 v[46:47], v[238:239], v[50:51], v[46:47] op_sel_hi:[0,1,1]
	v_lshlrev_b32_e32 v50, 16, v210
	v_and_b32_e32 v51, 0xffff0000, v210
	v_lshlrev_b32_e32 v52, 16, v211
	v_and_b32_e32 v53, 0xffff0000, v211
	v_pk_fma_f32 v[52:53], v[238:239], v[52:53], v[44:45] op_sel_hi:[0,1,1]
	v_pk_fma_f32 v[44:45], v[238:239], v[50:51], v[42:43] op_sel_hi:[0,1,1]
	v_mul_f32_e32 v42, v47, v47
	v_mul_f32_e32 v43, v49, v49
	v_fmac_f32_e32 v42, v46, v46
	v_fmac_f32_e32 v43, v48, v48
	v_add_f32_e32 v42, v42, v43
	v_mul_f32_e32 v43, v45, v45
	v_mul_f32_e32 v50, v53, v53
	v_fmac_f32_e32 v43, v44, v44
	v_fmac_f32_e32 v50, v52, v52
	v_add_f32_e32 v43, v43, v50
	v_add_f32_e32 v54, v42, v43
	v_lshl_add_u64 v[42:43], s[12:13], 0, v[106:107]
	v_lshl_add_u64 v[50:51], v[154:155], 1, v[42:43]
	v_cvt_pk_bf16_f32 v42, v46, v47
	v_cvt_pk_bf16_f32 v43, v48, v49
	v_cvt_pk_bf16_f32 v44, v44, v45
	v_cvt_pk_bf16_f32 v45, v52, v53
	global_store_dwordx4 v[50:51], v[42:45], off sc1
	s_nop 1
	v_lshlrev_b32_e32 v42, 16, v212
	v_and_b32_e32 v43, 0xffff0000, v212
	v_lshlrev_b32_e32 v44, 16, v213
	v_and_b32_e32 v45, 0xffff0000, v213
	v_pk_fma_f32 v[40:41], v[238:239], v[44:45], v[40:41] op_sel_hi:[0,1,1]
	v_pk_fma_f32 v[38:39], v[238:239], v[42:43], v[38:39] op_sel_hi:[0,1,1]
	v_lshlrev_b32_e32 v44, 16, v215
	v_and_b32_e32 v45, 0xffff0000, v215
	v_lshlrev_b32_e32 v42, 16, v214
	v_and_b32_e32 v43, 0xffff0000, v214
	v_pk_fma_f32 v[44:45], v[238:239], v[44:45], v[36:37] op_sel_hi:[0,1,1]
	v_mul_f32_e32 v36, v39, v39
	v_mul_f32_e32 v37, v41, v41
	v_pk_fma_f32 v[34:35], v[238:239], v[42:43], v[34:35] op_sel_hi:[0,1,1]
	v_fmac_f32_e32 v36, v38, v38
	v_fmac_f32_e32 v37, v40, v40
	v_add_f32_e32 v36, v36, v37
	v_mul_f32_e32 v37, v35, v35
	v_mul_f32_e32 v42, v45, v45
	v_fmac_f32_e32 v37, v34, v34
	v_fmac_f32_e32 v42, v44, v44
	v_add_f32_e32 v37, v37, v42
	v_add_f32_e32 v36, v36, v37
	v_add_f32_e32 v46, v54, v36
	ds_bpermute_b32 v47, v114, v46
	v_cvt_pk_bf16_f32 v36, v38, v39
	v_cvt_pk_bf16_f32 v38, v34, v35
	v_lshl_add_u64 v[42:43], v[50:51], 0, s[8:9]
	v_cvt_pk_bf16_f32 v37, v40, v41
	s_waitcnt lgkmcnt(0)
	v_add_f32_e32 v34, v46, v47
	ds_bpermute_b32 v35, v115, v34
	v_cvt_pk_bf16_f32 v39, v44, v45
	global_store_dwordx4 v[42:43], v[36:39], off sc1
	s_nop 1
	s_and_saveexec_b64 s[8:9], vcc
	s_cbranch_execz .LBB0_782
	v_lshl_add_u64 v[36:37], v[102:103], 2, s[10:11]
	s_waitcnt lgkmcnt(0)
	v_add_f32_e32 v34, v34, v35
	global_atomic_add_f32 v[36:37], v34, off
; __device__ __forceinline__ float dot4(f32x4 a) { return (a[0] * a[0] + a[1] * a[1]) + (a[2] * a[2] + a[3] * a[3]); }
; __device__ __forceinline__ void store16_wt(void* p, u32x4 v) { asm volatile("global_store_dwordx4 %0, %1, off sc1\n\ts_nop 1" :: "v"(p), "v"(v) : "memory"); }
; __device__ __forceinline__ u32x4 pack8(f32x4 a, f32x4 b) { u32x4 w; w.x = cvt_pk_bf16(a[0], a[1]); w.y = cvt_pk_bf16(a[2], a[3]); w.z = cvt_pk_bf16(b[0], b[1]); w.w = cvt_pk_bf16(b[2], b[3]); return w; }
;     __device__ __forceinline__ void operator()(const f32x4 (&acc)[2][2][4][2], const Unit& u, int wr, int wc, int fr, int fq) const {
;     ...
;             for (int m = 0; m < 4; ++m) {
;                 const int row = row0 + ai * HALF + m * 16;
;                 float ss = 0.f; const float r = rms[m];
; #pragma unroll
;                 for (int bj = 0; bj < 2; ++bj) { const int col = col0 + bj * HALF; const u32x4 w = xw[m][bj];
;                     const f32x4 a = (f32x4){__builtin_bit_cast(float, w.x << 16), __builtin_bit_cast(float, w.x & 0xffff0000u), __builtin_bit_cast(float, w.y << 16), __builtin_bit_cast(float, w.y & 0xffff0000u)} * r + acc[ai][bj][m][0],
;                                 b = (f32x4){__builtin_bit_cast(float, w.z << 16), __builtin_bit_cast(float, w.z & 0xffff0000u), __builtin_bit_cast(float, w.w << 16), __builtin_bit_cast(float, w.w & 0xffff0000u)} * r + acc[ai][bj][m][1];
;                     ss += dot4(a) + dot4(b);
;                     store16_wt(X1B + (size_t)row * 1024 + col, pack8(a, b)); }
;                 ss += __shfl_xor(ss, 16); ss += __shfl_xor(ss, 32);
;                 if (fq == 0) __hip_atomic_fetch_add(RSS + row, ss, __ATOMIC_RELAXED, __HIP_MEMORY_SCOPE_AGENT);
.LBB0_782:
	s_or_b64 exec, exec, s[8:9]
	v_lshlrev_b32_e32 v34, 16, v216
	s_waitcnt lgkmcnt(0)
	v_and_b32_e32 v35, 0xffff0000, v216
	v_lshlrev_b32_e32 v36, 16, v217
	v_and_b32_e32 v37, 0xffff0000, v217
	v_pk_fma_f32 v[32:33], v[240:241], v[36:37], v[32:33] op_sel_hi:[0,1,1]
	v_pk_fma_f32 v[30:31], v[240:241], v[34:35], v[30:31] op_sel_hi:[0,1,1]
	v_lshlrev_b32_e32 v34, 16, v218
	v_and_b32_e32 v35, 0xffff0000, v218
	v_lshlrev_b32_e32 v36, 16, v219
	v_and_b32_e32 v37, 0xffff0000, v219
	v_pk_fma_f32 v[36:37], v[240:241], v[36:37], v[28:29] op_sel_hi:[0,1,1]
	v_pk_fma_f32 v[28:29], v[240:241], v[34:35], v[26:27] op_sel_hi:[0,1,1]
	v_mul_f32_e32 v26, v31, v31
	v_mul_f32_e32 v27, v33, v33
	v_fmac_f32_e32 v26, v30, v30
	v_fmac_f32_e32 v27, v32, v32
	v_add_f32_e32 v26, v26, v27
	v_mul_f32_e32 v27, v29, v29
	v_mul_f32_e32 v34, v37, v37
	v_fmac_f32_e32 v27, v28, v28
	v_fmac_f32_e32 v34, v36, v36
	v_add_f32_e32 v27, v27, v34
	v_add_f32_e32 v38, v26, v27
	v_lshl_add_u64 v[26:27], s[12:13], 0, v[100:101]
	v_lshl_add_u64 v[34:35], v[154:155], 1, v[26:27]
	v_cvt_pk_bf16_f32 v26, v30, v31
	v_cvt_pk_bf16_f32 v27, v32, v33
	v_cvt_pk_bf16_f32 v28, v28, v29
	v_cvt_pk_bf16_f32 v29, v36, v37
	global_store_dwordx4 v[34:35], v[26:29], off sc1
	s_nop 1
	v_lshlrev_b32_e32 v26, 16, v220
	v_and_b32_e32 v27, 0xffff0000, v220
	v_lshlrev_b32_e32 v28, 16, v221
	v_and_b32_e32 v29, 0xffff0000, v221
	v_pk_fma_f32 v[24:25], v[240:241], v[28:29], v[24:25] op_sel_hi:[0,1,1]
	v_pk_fma_f32 v[22:23], v[240:241], v[26:27], v[22:23] op_sel_hi:[0,1,1]
	v_lshlrev_b32_e32 v28, 16, v223
	v_and_b32_e32 v29, 0xffff0000, v223
	v_lshlrev_b32_e32 v26, 16, v222
	v_and_b32_e32 v27, 0xffff0000, v222
	v_pk_fma_f32 v[28:29], v[240:241], v[28:29], v[20:21] op_sel_hi:[0,1,1]
	v_mul_f32_e32 v20, v23, v23
	v_mul_f32_e32 v21, v25, v25
	v_pk_fma_f32 v[18:19], v[240:241], v[26:27], v[18:19] op_sel_hi:[0,1,1]
	v_fmac_f32_e32 v20, v22, v22
	v_fmac_f32_e32 v21, v24, v24
	v_add_f32_e32 v20, v20, v21
	v_mul_f32_e32 v21, v19, v19
	v_mul_f32_e32 v26, v29, v29
	v_fmac_f32_e32 v21, v18, v18
	v_fmac_f32_e32 v26, v28, v28
	v_add_f32_e32 v21, v21, v26
	v_add_f32_e32 v20, v20, v21
	v_add_f32_e32 v30, v38, v20
	ds_bpermute_b32 v31, v114, v30
	v_cvt_pk_bf16_f32 v20, v22, v23
	v_cvt_pk_bf16_f32 v22, v18, v19
	s_mov_b64 s[8:9], 0x100
	v_lshl_add_u64 v[26:27], v[34:35], 0, s[8:9]
	s_waitcnt lgkmcnt(0)
	v_add_f32_e32 v18, v30, v31
	ds_bpermute_b32 v19, v115, v18
	v_cvt_pk_bf16_f32 v21, v24, v25
	v_cvt_pk_bf16_f32 v23, v28, v29
	global_store_dwordx4 v[26:27], v[20:23], off sc1
	s_nop 1
	s_and_saveexec_b64 s[14:15], vcc
	s_cbranch_execz .LBB0_784
	v_lshl_add_u64 v[20:21], v[96:97], 2, s[10:11]
	s_waitcnt lgkmcnt(0)
	v_add_f32_e32 v18, v18, v19
	global_atomic_add_f32 v[20:21], v18, off
.LBB0_784:
	s_or_b64 exec, exec, s[14:15]
	v_lshlrev_b32_e32 v18, 16, v224
	s_waitcnt lgkmcnt(0)
	v_and_b32_e32 v19, 0xffff0000, v224
	v_lshlrev_b32_e32 v20, 16, v225
	v_and_b32_e32 v21, 0xffff0000, v225
	v_pk_fma_f32 v[16:17], v[244:245], v[20:21], v[16:17] op_sel_hi:[0,1,1]
	v_pk_fma_f32 v[14:15], v[244:245], v[18:19], v[14:15] op_sel_hi:[0,1,1]
	v_lshlrev_b32_e32 v18, 16, v226
	v_and_b32_e32 v19, 0xffff0000, v226
	v_lshlrev_b32_e32 v20, 16, v227
	v_and_b32_e32 v21, 0xffff0000, v227
	v_pk_fma_f32 v[20:21], v[244:245], v[20:21], v[12:13] op_sel_hi:[0,1,1]
	v_pk_fma_f32 v[12:13], v[244:245], v[18:19], v[10:11] op_sel_hi:[0,1,1]
	v_mul_f32_e32 v10, v15, v15
	v_mul_f32_e32 v11, v17, v17
	v_fmac_f32_e32 v10, v14, v14
	v_fmac_f32_e32 v11, v16, v16
	v_add_f32_e32 v10, v10, v11
	v_mul_f32_e32 v11, v13, v13
	v_mul_f32_e32 v18, v21, v21
	v_fmac_f32_e32 v11, v12, v12
	v_fmac_f32_e32 v18, v20, v20
	v_add_f32_e32 v11, v11, v18
	v_add_f32_e32 v22, v10, v11
	v_lshl_add_u64 v[10:11], s[12:13], 0, v[94:95]
	v_lshl_add_u64 v[18:19], v[154:155], 1, v[10:11]
	v_cvt_pk_bf16_f32 v10, v14, v15
	v_cvt_pk_bf16_f32 v11, v16, v17
	v_cvt_pk_bf16_f32 v12, v12, v13
	v_cvt_pk_bf16_f32 v13, v20, v21
	global_store_dwordx4 v[18:19], v[10:13], off sc1
	s_nop 1
	v_lshlrev_b32_e32 v10, 16, v232
	v_and_b32_e32 v11, 0xffff0000, v232
	v_lshlrev_b32_e32 v12, 16, v233
	v_and_b32_e32 v13, 0xffff0000, v233
	v_pk_fma_f32 v[8:9], v[244:245], v[12:13], v[8:9] op_sel_hi:[0,1,1]
	v_pk_fma_f32 v[6:7], v[244:245], v[10:11], v[6:7] op_sel_hi:[0,1,1]
	v_lshlrev_b32_e32 v12, 16, v235
	v_and_b32_e32 v13, 0xffff0000, v235
	v_lshlrev_b32_e32 v10, 16, v234
	v_and_b32_e32 v11, 0xffff0000, v234
	v_pk_fma_f32 v[12:13], v[244:245], v[12:13], v[4:5] op_sel_hi:[0,1,1]
	v_mul_f32_e32 v4, v7, v7
	v_mul_f32_e32 v5, v9, v9
	v_pk_fma_f32 v[2:3], v[244:245], v[10:11], v[2:3] op_sel_hi:[0,1,1]
	v_fmac_f32_e32 v4, v6, v6
	v_fmac_f32_e32 v5, v8, v8
	v_add_f32_e32 v4, v4, v5
	v_mul_f32_e32 v5, v3, v3
	v_mul_f32_e32 v10, v13, v13
	v_fmac_f32_e32 v5, v2, v2
	v_fmac_f32_e32 v10, v12, v12
	v_add_f32_e32 v5, v5, v10
	v_add_f32_e32 v4, v4, v5
	v_add_f32_e32 v14, v22, v4
	ds_bpermute_b32 v15, v114, v14
	v_cvt_pk_bf16_f32 v4, v6, v7
	v_cvt_pk_bf16_f32 v6, v2, v3
	v_lshl_add_u64 v[10:11], v[18:19], 0, s[8:9]
	v_cvt_pk_bf16_f32 v5, v8, v9
	s_waitcnt lgkmcnt(0)
	v_add_f32_e32 v2, v14, v15
	ds_bpermute_b32 v3, v115, v2
	v_cvt_pk_bf16_f32 v7, v12, v13
	global_store_dwordx4 v[10:11], v[4:7], off sc1
	s_nop 1
	s_and_saveexec_b64 s[8:9], vcc
	s_cbranch_execz .LBB0_786
	v_lshl_add_u64 v[4:5], v[90:91], 2, s[10:11]
	s_waitcnt lgkmcnt(0)
	v_add_f32_e32 v2, v2, v3
	global_atomic_add_f32 v[4:5], v2, off
